# Resid HALFM tail loop: LDS reads issued ahead of the DMA pieces, address SALU moved into the MFMA block
# speedup vs baseline: 1.0251x; 1.0016x over previous
.LBB0_786:
	v_mov_b32_e32 v39, v0
	v_lshl_add_u64 v[10:11], s[4:5], 0, v[38:39]
	v_mov_b32_e32 v35, v0
	v_lshl_add_u64 v[12:13], s[4:5], 0, v[34:35]
	v_mov_b32_e32 v41, v0
	s_add_i32 m0, s20, 0x18000
	v_lshl_add_u64 v[10:11], v[10:11], 0, s[76:77]
	v_lshl_add_u64 v[18:19], s[6:7], 0, v[40:41]
	v_mov_b32_e32 v37, v0
	s_waitcnt vmcnt(2)
	s_barrier
	global_load_lds_dwordx4 v[10:11], off
	v_lshl_add_u64 v[10:11], v[12:13], 0, s[76:77]
	s_add_i32 m0, s20, 0x1a000
	s_add_i32 s31, s20, 0x8000
	v_lshl_add_u64 v[20:21], s[6:7], 0, v[36:37]
	global_load_lds_dwordx4 v[10:11], off
	v_lshl_add_u64 v[10:11], v[18:19], 0, s[76:77]
	s_mov_b32 m0, s31
	s_add_i32 s34, s20, 0xa000
	v_lshl_add_u64 v[14:15], s[8:9], 0, v[38:39]
	global_load_lds_dwordx4 v[10:11], off
	v_lshl_add_u64 v[10:11], v[20:21], 0, s[76:77]
	s_mov_b32 m0, s34
	v_lshl_add_u64 v[16:17], s[8:9], 0, v[34:35]
	global_load_lds_dwordx4 v[10:11], off
	s_add_i32 m0, s20, 0x1c000
	v_lshl_add_u64 v[10:11], v[14:15], 0, s[76:77]
	global_load_lds_dwordx4 v[10:11], off
	v_lshl_add_u64 v[10:11], v[16:17], 0, s[76:77]
	s_add_i32 m0, s20, 0x1e000
	v_bfe_u32 v1, v5, 4, 2
	global_load_lds_dwordx4 v[10:11], off
	v_and_b32_e32 v9, 15, v5
	v_lshlrev_b32_e32 v22, 4, v1
	v_lshlrev_b32_e32 v5, 2, v5
	v_lshl_or_b32 v114, s15, 6, v9
	v_lshl_or_b32 v9, v9, 6, v22
	s_lshl_b32 s0, s15, 13
	v_and_b32_e32 v5, 32, v5
	v_bitop3_b32 v22, v9, s0, v5 bitop3:0xde
	s_lshl_b32 s0, s14, 5
	s_and_b32 s21, s0, 0x60
	s_lshl_b32 s0, s21, 7
	v_bitop3_b32 v54, v9, s0, v5 bitop3:0xde
	v_readlane_b32 s0, v254, 56
	s_add_i32 s35, s36, -2
	s_mul_i32 s0, s0, s1
	s_add_u32 s0, s10, s0
	s_addc_u32 s1, s11, 0
	s_add_u32 s0, s38, s0
	s_addc_u32 s1, s37, s1
	s_add_u32 s8, s0, 0x80
	v_add_u32_e32 v2, v4, v2
	s_waitcnt vmcnt(6)
	v_add_u32_e32 v5, v8, v6
	s_addc_u32 s9, s1, 0
	v_add_lshl_u32 v2, v2, v3, 1
	v_mov_b32_e32 v3, v0
	v_add_lshl_u32 v6, v5, v7, 1
	v_mov_b32_e32 v7, v0
	v_lshl_add_u64 v[52:53], s[8:9], 0, v[2:3]
	v_mov_b32_e32 v2, 0
	v_lshl_add_u64 v[50:51], s[8:9], 0, v[6:7]
	s_mov_b32 s14, 0
	s_mov_b64 s[8:9], 0
	v_add_u32_e32 v55, 0, v22
	v_mov_b32_e32 v3, v2
	v_mov_b32_e32 v4, v2
	v_mov_b32_e32 v5, v2
	v_mov_b32_e32 v6, v2
	v_mov_b32_e32 v7, v2
	v_mov_b32_e32 v8, v2
	v_mov_b32_e32 v9, v2
	v_mov_b32_e32 v18, v2
	v_mov_b32_e32 v19, v2
	v_mov_b32_e32 v20, v2
	v_mov_b32_e32 v21, v2
	v_mov_b32_e32 v22, v2
	v_mov_b32_e32 v23, v2
	v_mov_b32_e32 v24, v2
	v_mov_b32_e32 v25, v2
	v_mov_b32_e32 v42, v2
	v_mov_b32_e32 v43, v2
	v_mov_b32_e32 v44, v2
	v_mov_b32_e32 v45, v2
	v_mov_b32_e32 v46, v2
	v_mov_b32_e32 v47, v2
	v_mov_b32_e32 v48, v2
	v_mov_b32_e32 v49, v2
	v_mov_b32_e32 v82, v2
	v_mov_b32_e32 v83, v2
	v_mov_b32_e32 v84, v2
	v_mov_b32_e32 v85, v2
	v_mov_b32_e32 v86, v2
	v_mov_b32_e32 v87, v2
	v_mov_b32_e32 v88, v2
	v_mov_b32_e32 v89, v2
	v_mov_b32_e32 v10, v2
	v_mov_b32_e32 v11, v2
	v_mov_b32_e32 v12, v2
	v_mov_b32_e32 v13, v2
	v_mov_b32_e32 v14, v2
	v_mov_b32_e32 v15, v2
	v_mov_b32_e32 v16, v2
	v_mov_b32_e32 v17, v2
	v_mov_b32_e32 v26, v2
	v_mov_b32_e32 v27, v2
	v_mov_b32_e32 v28, v2
	v_mov_b32_e32 v29, v2
	v_mov_b32_e32 v30, v2
	v_mov_b32_e32 v31, v2
	v_mov_b32_e32 v32, v2
	v_mov_b32_e32 v33, v2
	v_mov_b32_e32 v70, v2
	v_mov_b32_e32 v71, v2
	v_mov_b32_e32 v72, v2
	v_mov_b32_e32 v73, v2
	v_mov_b32_e32 v78, v2
	v_mov_b32_e32 v79, v2
	v_mov_b32_e32 v80, v2
	v_mov_b32_e32 v81, v2
	v_mov_b32_e32 v90, v2
	v_mov_b32_e32 v91, v2
	v_mov_b32_e32 v92, v2
	v_mov_b32_e32 v93, v2
	v_mov_b32_e32 v94, v2
	v_mov_b32_e32 v95, v2
	v_mov_b32_e32 v96, v2
	v_mov_b32_e32 v97, v2
	s_barrier
	s_movk_i32 s8, 0x100
	s_lshl_b32 s9, s36, 7
	s_mov_b32 s14, 0
	v_add_u32_e32 v68, 0x10000, v54
	v_add_u32_e32 v69, 0x21c00, v54
	s_add_u32 s40, s4, s8
	s_addc_u32 s41, s5, 0
	s_add_u32 s42, s40, s12
	s_addc_u32 s43, s41, 0
	s_add_u32 s10, s6, s8
	s_addc_u32 s11, s7, 0
	s_addk_i32 s8, 0x80
	s_cmp_eq_u32 s8, s9
	s_cselect_b32 s8, 0, s8
.LBB0_787:
	s_add_i32 m0, s20, 0xc000
	ds_read_b128 v[56:59], v68 offset:0
	ds_read_b128 v[60:63], v68 offset:1024
	ds_read_b128 v[64:67], v68 offset:2048
	ds_read_b128 v[74:77], v68 offset:3072
	global_load_lds_dwordx4 v38, s[40:41]
	s_add_i32 m0, s20, 0xe000
	ds_read_b128 v[116:119], v55 offset:0
	ds_read_b128 v[120:123], v55 offset:1024
	ds_read_b128 v[124:127], v55 offset:2048
	global_load_lds_dwordx4 v34, s[40:41]
	s_add_i32 m0, s20, 0x21c00
	ds_read_b128 v[128:131], v55 offset:3072
	ds_read_b128 v[132:135], v55 offset:4096
	ds_read_b128 v[136:139], v55 offset:5120
	global_load_lds_dwordx4 v38, s[42:43]
	s_add_i32 m0, s20, 0x23c00
	ds_read_b128 v[140:143], v55 offset:6144
	ds_read_b128 v[144:147], v55 offset:7168
	global_load_lds_dwordx4 v34, s[42:43]
	s_add_i32 m0, s20, 0x4000
	ds_read_b128 v[98:101], v68 offset:16384
	ds_read_b128 v[102:105], v68 offset:17408
	global_load_lds_dwordx4 v40, s[10:11]
	s_add_i32 m0, s20, 0x6000
	ds_read_b128 v[106:109], v68 offset:18432
	ds_read_b128 v[110:113], v68 offset:19456
	global_load_lds_dwordx4 v36, s[10:11]
	s_waitcnt vmcnt(6)
	s_waitcnt lgkmcnt(0)
	s_barrier
	s_setprio 1
	v_mfma_f32_16x16x32_bf16 v[94:97], v[56:59], v[116:119], v[94:97]
	v_mfma_f32_16x16x32_bf16 v[90:93], v[64:67], v[116:119], v[90:93]
	v_mfma_f32_16x16x32_bf16 v[78:81], v[56:59], v[124:127], v[78:81]
	s_add_u32 s40, s4, s8
	v_mfma_f32_16x16x32_bf16 v[70:73], v[64:67], v[124:127], v[70:73]
	s_addc_u32 s41, s5, 0
	v_mfma_f32_16x16x32_bf16 v[30:33], v[56:59], v[132:135], v[30:33]
	s_add_u32 s42, s40, s12
	v_mfma_f32_16x16x32_bf16 v[26:29], v[64:67], v[132:135], v[26:29]
	s_addc_u32 s43, s41, 0
	v_mfma_f32_16x16x32_bf16 v[14:17], v[56:59], v[140:143], v[14:17]
	s_add_u32 s10, s6, s8
	v_mfma_f32_16x16x32_bf16 v[10:13], v[64:67], v[140:143], v[10:13]
	s_addc_u32 s11, s7, 0
	v_mfma_f32_16x16x32_bf16 v[94:97], v[60:63], v[120:123], v[94:97]
	s_addk_i32 s8, 0x80
	v_mfma_f32_16x16x32_bf16 v[90:93], v[74:77], v[120:123], v[90:93]
	s_cmp_eq_u32 s8, s9
	v_mfma_f32_16x16x32_bf16 v[78:81], v[60:63], v[128:131], v[78:81]
	s_cselect_b32 s8, 0, s8
	v_mfma_f32_16x16x32_bf16 v[70:73], v[74:77], v[128:131], v[70:73]
	v_mfma_f32_16x16x32_bf16 v[30:33], v[60:63], v[136:139], v[30:33]
	v_mfma_f32_16x16x32_bf16 v[26:29], v[74:77], v[136:139], v[26:29]
	v_mfma_f32_16x16x32_bf16 v[14:17], v[60:63], v[144:147], v[14:17]
	v_mfma_f32_16x16x32_bf16 v[10:13], v[74:77], v[144:147], v[10:13]
	v_mfma_f32_16x16x32_bf16 v[86:89], v[98:101], v[116:119], v[86:89]
	v_mfma_f32_16x16x32_bf16 v[82:85], v[106:109], v[116:119], v[82:85]
	v_mfma_f32_16x16x32_bf16 v[46:49], v[98:101], v[124:127], v[46:49]
	v_mfma_f32_16x16x32_bf16 v[42:45], v[106:109], v[124:127], v[42:45]
	v_mfma_f32_16x16x32_bf16 v[22:25], v[98:101], v[132:135], v[22:25]
	v_mfma_f32_16x16x32_bf16 v[18:21], v[106:109], v[132:135], v[18:21]
	v_mfma_f32_16x16x32_bf16 v[6:9], v[98:101], v[140:143], v[6:9]
	v_mfma_f32_16x16x32_bf16 v[2:5], v[106:109], v[140:143], v[2:5]
	v_mfma_f32_16x16x32_bf16 v[86:89], v[102:105], v[120:123], v[86:89]
	v_mfma_f32_16x16x32_bf16 v[82:85], v[110:113], v[120:123], v[82:85]
	v_mfma_f32_16x16x32_bf16 v[46:49], v[102:105], v[128:131], v[46:49]
	v_mfma_f32_16x16x32_bf16 v[42:45], v[110:113], v[128:131], v[42:45]
	v_mfma_f32_16x16x32_bf16 v[22:25], v[102:105], v[136:139], v[22:25]
	v_mfma_f32_16x16x32_bf16 v[18:21], v[110:113], v[136:139], v[18:21]
	v_mfma_f32_16x16x32_bf16 v[6:9], v[102:105], v[144:147], v[6:9]
	v_mfma_f32_16x16x32_bf16 v[2:5], v[110:113], v[144:147], v[2:5]
	s_setprio 0
	s_barrier
	s_add_i32 s14, s14, 1
	s_cmp_ge_u32 s14, s36
	s_cbranch_scc1 .Lrt_done
	s_add_i32 m0, s20, 0x10000
	ds_read_b128 v[56:59], v68 offset:32768
	ds_read_b128 v[60:63], v68 offset:33792
	ds_read_b128 v[64:67], v68 offset:34816
	ds_read_b128 v[74:77], v68 offset:35840
	global_load_lds_dwordx4 v38, s[40:41]
	s_add_i32 m0, s20, 0x12000
	ds_read_b128 v[116:119], v55 offset:32768
	ds_read_b128 v[120:123], v55 offset:33792
	ds_read_b128 v[124:127], v55 offset:34816
	global_load_lds_dwordx4 v34, s[40:41]
	s_add_i32 m0, s20, 0x14000
	ds_read_b128 v[128:131], v55 offset:35840
	ds_read_b128 v[132:135], v55 offset:36864
	ds_read_b128 v[136:139], v55 offset:37888
	global_load_lds_dwordx4 v38, s[42:43]
	s_add_i32 m0, s20, 0x16000
	ds_read_b128 v[140:143], v55 offset:38912
	ds_read_b128 v[144:147], v55 offset:39936
	global_load_lds_dwordx4 v34, s[42:43]
	s_add_i32 m0, s20, 0x0
	ds_read_b128 v[98:101], v68 offset:49152
	ds_read_b128 v[102:105], v68 offset:50176
	global_load_lds_dwordx4 v40, s[10:11]
	s_add_i32 m0, s20, 0x2000
	ds_read_b128 v[106:109], v68 offset:51200
	ds_read_b128 v[110:113], v68 offset:52224
	global_load_lds_dwordx4 v36, s[10:11]
	s_waitcnt vmcnt(6)
	s_waitcnt lgkmcnt(0)
	s_barrier
	s_setprio 1
	v_mfma_f32_16x16x32_bf16 v[94:97], v[56:59], v[116:119], v[94:97]
	v_mfma_f32_16x16x32_bf16 v[90:93], v[64:67], v[116:119], v[90:93]
	v_mfma_f32_16x16x32_bf16 v[78:81], v[56:59], v[124:127], v[78:81]
	s_add_u32 s40, s4, s8
	v_mfma_f32_16x16x32_bf16 v[70:73], v[64:67], v[124:127], v[70:73]
	s_addc_u32 s41, s5, 0
	v_mfma_f32_16x16x32_bf16 v[30:33], v[56:59], v[132:135], v[30:33]
	s_add_u32 s42, s40, s12
	v_mfma_f32_16x16x32_bf16 v[26:29], v[64:67], v[132:135], v[26:29]
	s_addc_u32 s43, s41, 0
	v_mfma_f32_16x16x32_bf16 v[14:17], v[56:59], v[140:143], v[14:17]
	s_add_u32 s10, s6, s8
	v_mfma_f32_16x16x32_bf16 v[10:13], v[64:67], v[140:143], v[10:13]
	s_addc_u32 s11, s7, 0
	v_mfma_f32_16x16x32_bf16 v[94:97], v[60:63], v[120:123], v[94:97]
	s_addk_i32 s8, 0x80
	v_mfma_f32_16x16x32_bf16 v[90:93], v[74:77], v[120:123], v[90:93]
	s_cmp_eq_u32 s8, s9
	v_mfma_f32_16x16x32_bf16 v[78:81], v[60:63], v[128:131], v[78:81]
	s_cselect_b32 s8, 0, s8
	v_mfma_f32_16x16x32_bf16 v[70:73], v[74:77], v[128:131], v[70:73]
	v_mfma_f32_16x16x32_bf16 v[30:33], v[60:63], v[136:139], v[30:33]
	v_mfma_f32_16x16x32_bf16 v[26:29], v[74:77], v[136:139], v[26:29]
	v_mfma_f32_16x16x32_bf16 v[14:17], v[60:63], v[144:147], v[14:17]
	v_mfma_f32_16x16x32_bf16 v[10:13], v[74:77], v[144:147], v[10:13]
	v_mfma_f32_16x16x32_bf16 v[86:89], v[98:101], v[116:119], v[86:89]
	v_mfma_f32_16x16x32_bf16 v[82:85], v[106:109], v[116:119], v[82:85]
	v_mfma_f32_16x16x32_bf16 v[46:49], v[98:101], v[124:127], v[46:49]
	v_mfma_f32_16x16x32_bf16 v[42:45], v[106:109], v[124:127], v[42:45]
	v_mfma_f32_16x16x32_bf16 v[22:25], v[98:101], v[132:135], v[22:25]
	v_mfma_f32_16x16x32_bf16 v[18:21], v[106:109], v[132:135], v[18:21]
	v_mfma_f32_16x16x32_bf16 v[6:9], v[98:101], v[140:143], v[6:9]
	v_mfma_f32_16x16x32_bf16 v[2:5], v[106:109], v[140:143], v[2:5]
	v_mfma_f32_16x16x32_bf16 v[86:89], v[102:105], v[120:123], v[86:89]
	v_mfma_f32_16x16x32_bf16 v[82:85], v[110:113], v[120:123], v[82:85]
	v_mfma_f32_16x16x32_bf16 v[46:49], v[102:105], v[128:131], v[46:49]
	v_mfma_f32_16x16x32_bf16 v[42:45], v[110:113], v[128:131], v[42:45]
	v_mfma_f32_16x16x32_bf16 v[22:25], v[102:105], v[136:139], v[22:25]
	v_mfma_f32_16x16x32_bf16 v[18:21], v[110:113], v[136:139], v[18:21]
	v_mfma_f32_16x16x32_bf16 v[6:9], v[102:105], v[144:147], v[6:9]
	v_mfma_f32_16x16x32_bf16 v[2:5], v[110:113], v[144:147], v[2:5]
	s_setprio 0
	s_barrier
	s_add_i32 s14, s14, 1
	s_cmp_ge_u32 s14, s36
	s_cbranch_scc1 .Lrt_done
	s_add_i32 m0, s20, 0x18000
	ds_read_b128 v[56:59], v54 offset:49152
	ds_read_b128 v[60:63], v54 offset:50176
	ds_read_b128 v[64:67], v54 offset:51200
	ds_read_b128 v[74:77], v54 offset:52224
	global_load_lds_dwordx4 v38, s[40:41]
	s_add_i32 m0, s20, 0x1a000
	ds_read_b128 v[116:119], v55 offset:16384
	ds_read_b128 v[120:123], v55 offset:17408
	ds_read_b128 v[124:127], v55 offset:18432
	global_load_lds_dwordx4 v34, s[40:41]
	s_add_i32 m0, s20, 0x1c000
	ds_read_b128 v[128:131], v55 offset:19456
	ds_read_b128 v[132:135], v55 offset:20480
	ds_read_b128 v[136:139], v55 offset:21504
	global_load_lds_dwordx4 v38, s[42:43]
	s_add_i32 m0, s20, 0x1e000
	ds_read_b128 v[140:143], v55 offset:22528
	ds_read_b128 v[144:147], v55 offset:23552
	global_load_lds_dwordx4 v34, s[42:43]
	s_add_i32 m0, s20, 0x8000
	ds_read_b128 v[98:101], v69 offset:0
	ds_read_b128 v[102:105], v69 offset:1024
	global_load_lds_dwordx4 v40, s[10:11]
	s_add_i32 m0, s20, 0xa000
	ds_read_b128 v[106:109], v69 offset:2048
	ds_read_b128 v[110:113], v69 offset:3072
	global_load_lds_dwordx4 v36, s[10:11]
	s_waitcnt vmcnt(6)
	s_waitcnt lgkmcnt(0)
	s_barrier
	s_setprio 1
	v_mfma_f32_16x16x32_bf16 v[94:97], v[56:59], v[116:119], v[94:97]
	v_mfma_f32_16x16x32_bf16 v[90:93], v[64:67], v[116:119], v[90:93]
	v_mfma_f32_16x16x32_bf16 v[78:81], v[56:59], v[124:127], v[78:81]
	s_add_u32 s40, s4, s8
	v_mfma_f32_16x16x32_bf16 v[70:73], v[64:67], v[124:127], v[70:73]
	s_addc_u32 s41, s5, 0
	v_mfma_f32_16x16x32_bf16 v[30:33], v[56:59], v[132:135], v[30:33]
	s_add_u32 s42, s40, s12
	v_mfma_f32_16x16x32_bf16 v[26:29], v[64:67], v[132:135], v[26:29]
	s_addc_u32 s43, s41, 0
	v_mfma_f32_16x16x32_bf16 v[14:17], v[56:59], v[140:143], v[14:17]
	s_add_u32 s10, s6, s8
	v_mfma_f32_16x16x32_bf16 v[10:13], v[64:67], v[140:143], v[10:13]
	s_addc_u32 s11, s7, 0
	v_mfma_f32_16x16x32_bf16 v[94:97], v[60:63], v[120:123], v[94:97]
	s_addk_i32 s8, 0x80
	v_mfma_f32_16x16x32_bf16 v[90:93], v[74:77], v[120:123], v[90:93]
	s_cmp_eq_u32 s8, s9
	v_mfma_f32_16x16x32_bf16 v[78:81], v[60:63], v[128:131], v[78:81]
	s_cselect_b32 s8, 0, s8
	v_mfma_f32_16x16x32_bf16 v[70:73], v[74:77], v[128:131], v[70:73]
	v_mfma_f32_16x16x32_bf16 v[30:33], v[60:63], v[136:139], v[30:33]
	v_mfma_f32_16x16x32_bf16 v[26:29], v[74:77], v[136:139], v[26:29]
	v_mfma_f32_16x16x32_bf16 v[14:17], v[60:63], v[144:147], v[14:17]
	v_mfma_f32_16x16x32_bf16 v[10:13], v[74:77], v[144:147], v[10:13]
	v_mfma_f32_16x16x32_bf16 v[86:89], v[98:101], v[116:119], v[86:89]
	v_mfma_f32_16x16x32_bf16 v[82:85], v[106:109], v[116:119], v[82:85]
	v_mfma_f32_16x16x32_bf16 v[46:49], v[98:101], v[124:127], v[46:49]
	v_mfma_f32_16x16x32_bf16 v[42:45], v[106:109], v[124:127], v[42:45]
	v_mfma_f32_16x16x32_bf16 v[22:25], v[98:101], v[132:135], v[22:25]
	v_mfma_f32_16x16x32_bf16 v[18:21], v[106:109], v[132:135], v[18:21]
	v_mfma_f32_16x16x32_bf16 v[6:9], v[98:101], v[140:143], v[6:9]
	v_mfma_f32_16x16x32_bf16 v[2:5], v[106:109], v[140:143], v[2:5]
	v_mfma_f32_16x16x32_bf16 v[86:89], v[102:105], v[120:123], v[86:89]
	v_mfma_f32_16x16x32_bf16 v[82:85], v[110:113], v[120:123], v[82:85]
	v_mfma_f32_16x16x32_bf16 v[46:49], v[102:105], v[128:131], v[46:49]
	v_mfma_f32_16x16x32_bf16 v[42:45], v[110:113], v[128:131], v[42:45]
	v_mfma_f32_16x16x32_bf16 v[22:25], v[102:105], v[136:139], v[22:25]
	v_mfma_f32_16x16x32_bf16 v[18:21], v[110:113], v[136:139], v[18:21]
	v_mfma_f32_16x16x32_bf16 v[6:9], v[102:105], v[144:147], v[6:9]
	v_mfma_f32_16x16x32_bf16 v[2:5], v[110:113], v[144:147], v[2:5]
	s_setprio 0
	s_barrier
	s_add_i32 s14, s14, 1
	s_cmp_lt_u32 s14, s36
	s_cbranch_scc1 .LBB0_787
